# v60 plus lean grid barrier on seams 1..9 (every leader polls the monotonic TOP counter; generation = seam index - ph_lo; no TOPGEN/XGEN hand-offs; compiled barrier kept as fallback when the census is
# speedup vs baseline: 1.0015x; 1.0015x over previous
; __device__ __forceinline__ unsigned xb_ld(unsigned* p)              { return __hip_atomic_load(p, __ATOMIC_RELAXED, __HIP_MEMORY_SCOPE_AGENT); }
; __device__ __forceinline__ unsigned xb_add(unsigned* p, unsigned v) { return __hip_atomic_fetch_add(p, v, __ATOMIC_RELAXED, __HIP_MEMORY_SCOPE_AGENT); }
; #define XB_SPIN(cond, bar) do { unsigned _sp = 0; while (cond) { __builtin_amdgcn_s_sleep(1); \
;     if ((++_sp & 255u) == 0u) { if (xb_ld(&(bar)[XB_TMO])) break; if (_sp > XB_SPIN_CAP) { atomicAdd(&(bar)[XB_TMO], 1u); break; } } } } while (0)
; #define SEAM(k) do { if (IN(k) && IN((k) + 1)) { xcd_barrier(bar, wave == 0 && mk_lane() == 0); } } while (0)
; __device__ __forceinline__ void xcd_barrier(const XcdBarrier& b, bool leader) {
;     asm volatile("s_waitcnt vmcnt(0)" ::: "memory");
;     __syncthreads();
;     if (leader) {
;         unsigned* bar = b.bar;
;         __builtin_amdgcn_s_waitcnt(0);
;         unsigned nloc = b.st[0], nx = b.st[1];
;         if (nloc == 0u) { xcd_barrier_complete(bar, b.x, nloc, nx); b.st[0] = nloc; b.st[1] = nx; }
;         const unsigned old = xb_add(&bar[XB_XSUB(b.x)], 1u);
;         const unsigned gen = old / nloc;
;         if (old + 1u == (gen + 1u) * nloc) {
;             __builtin_amdgcn_fence(__ATOMIC_RELEASE, "agent");
;             asm volatile("s_waitcnt vmcnt(0)" ::: "memory");
;             const unsigned og = xb_add(&bar[XB_TOP], 1u);
;             const unsigned tg = og / nx;
;             if (og + 1u == (tg + 1u) * nx) xb_add(&bar[XB_TOPGEN], 1u);
;             else XB_SPIN(xb_ld(&bar[XB_TOPGEN]) == tg, bar);
;             __builtin_amdgcn_fence(__ATOMIC_ACQUIRE, "agent");
;             xb_add(&bar[XB_XGEN(b.x)], 1u);
;             asm volatile("s_waitcnt vmcnt(0)" ::: "memory");
;         } else {
;             XB_SPIN(xb_ld(&bar[XB_XGEN(b.x)]) == gen, bar);
;             __builtin_amdgcn_fence(__ATOMIC_ACQUIRE, "agent");
;             asm volatile("s_waitcnt vmcnt(0)" ::: "memory");
;         }
;     }
;     __syncthreads();
; __global__ void __launch_bounds__(NWAVES * 64, 2) mk_fwd(Params P) {
;     ...
;     SEAM(1);
.LBB0_460:
	s_cmp_gt_i32 s75, 2
	s_cselect_b64 s[0:1], -1, 0
	s_and_b64 s[2:3], s[42:43], s[0:1]
	s_andn2_b64 vcc, exec, s[2:3]
	s_cbranch_vccnz .LBB0_512
	v_mov_b32_e32 v0, 0x20400
	ds_read_b32 v1, v0
	ds_read_b32 v2, v0 offset:4
	s_waitcnt vmcnt(0) lgkmcnt(0)
	v_readfirstlane_b32 s10, v1
	v_readfirstlane_b32 s11, v2
	s_cmp_eq_u32 s10, 0
	s_cbranch_scc1 .Lfb_old_1
	s_barrier
	v_readlane_b32 s14, v254, 4
	v_readlane_b32 s15, v254, 5
	s_cmp_lg_u64 s[14:15], 0
	s_cbranch_scc1 .Lfb_close_1
	s_mov_b64 s[12:13], exec
	s_mov_b64 exec, 1
	s_lshl_b32 s14, s92, 8
	s_add_u32 s38, s72, 0x311400
	s_addc_u32 s39, s73, 0
	s_add_u32 s38, s38, s14
	s_addc_u32 s39, s39, 0
	s_add_u32 s40, s72, 0x313400
	s_addc_u32 s41, s73, 0
	v_mov_b32_e32 v0, 0
	v_mov_b32_e32 v1, 1
	global_atomic_add v2, v0, v1, s[38:39] sc0
	s_sub_i32 s14, 2, s74
	s_mul_i32 s15, s14, s10
	s_mul_i32 s11, s14, s11
	s_waitcnt vmcnt(0)
	v_readfirstlane_b32 s14, v2
	s_add_i32 s14, s14, 1
	s_cmp_lg_u32 s14, s15
	s_cbranch_scc1 .Lfb_spin0_1
	buffer_wbl2 sc1
	s_waitcnt vmcnt(0)
	global_atomic_add v0, v1, s[40:41]
.Lfb_spin0_1:
	s_mov_b32 s15, 0
.Lfb_spin_1:
	global_load_dword v2, v0, s[40:41] sc1
	s_waitcnt vmcnt(0)
	v_readfirstlane_b32 s14, v2
	s_cmp_ge_u32 s14, s11
	s_cbranch_scc1 .Lfb_rel_1
	s_sleep 1
	s_add_i32 s15, s15, 1
	s_cmp_lt_u32 s15, 0x10000
	s_cbranch_scc1 .Lfb_spin_1
.Lfb_rel_1:
	buffer_inv sc1
	s_waitcnt vmcnt(0)
	s_mov_b64 exec, s[12:13]
.Lfb_close_1:
	s_barrier
	s_branch .LBB0_512
.Lfb_old_1:
	v_readlane_b32 s2, v254, 4
	v_readlane_b32 s3, v254, 5
	s_and_b64 vcc, exec, s[2:3]
	s_mov_b64 s[6:7], 0
	s_cbranch_vccnz .LBB0_463
	v_mov_b32_e32 v0, v212
	s_nop 0
	v_cmp_eq_u32_e32 vcc, 0, v0
	s_and_b64 s[6:7], vcc, exec

; __device__ __forceinline__ unsigned xb_ld(unsigned* p)              { return __hip_atomic_load(p, __ATOMIC_RELAXED, __HIP_MEMORY_SCOPE_AGENT); }
; __device__ __forceinline__ unsigned xb_add(unsigned* p, unsigned v) { return __hip_atomic_fetch_add(p, v, __ATOMIC_RELAXED, __HIP_MEMORY_SCOPE_AGENT); }
; #define XB_SPIN(cond, bar) do { unsigned _sp = 0; while (cond) { __builtin_amdgcn_s_sleep(1); \
;     if ((++_sp & 255u) == 0u) { if (xb_ld(&(bar)[XB_TMO])) break; if (_sp > XB_SPIN_CAP) { atomicAdd(&(bar)[XB_TMO], 1u); break; } } } } while (0)
; #define SEAM(k) do { if (IN(k) && IN((k) + 1)) { xcd_barrier(bar, wave == 0 && mk_lane() == 0); } } while (0)
; __device__ __forceinline__ void xcd_barrier(const XcdBarrier& b, bool leader) {
;     asm volatile("s_waitcnt vmcnt(0)" ::: "memory");
;     __syncthreads();
;     if (leader) {
;         unsigned* bar = b.bar;
;         __builtin_amdgcn_s_waitcnt(0);
;         unsigned nloc = b.st[0], nx = b.st[1];
;         if (nloc == 0u) { xcd_barrier_complete(bar, b.x, nloc, nx); b.st[0] = nloc; b.st[1] = nx; }
;         const unsigned old = xb_add(&bar[XB_XSUB(b.x)], 1u);
;         const unsigned gen = old / nloc;
;         if (old + 1u == (gen + 1u) * nloc) {
;             __builtin_amdgcn_fence(__ATOMIC_RELEASE, "agent");
;             asm volatile("s_waitcnt vmcnt(0)" ::: "memory");
;             const unsigned og = xb_add(&bar[XB_TOP], 1u);
;             const unsigned tg = og / nx;
;             if (og + 1u == (tg + 1u) * nx) xb_add(&bar[XB_TOPGEN], 1u);
;             else XB_SPIN(xb_ld(&bar[XB_TOPGEN]) == tg, bar);
;             __builtin_amdgcn_fence(__ATOMIC_ACQUIRE, "agent");
;             xb_add(&bar[XB_XGEN(b.x)], 1u);
; __global__ void __launch_bounds__(NWAVES * 64, 2) mk_fwd(Params P) {
;     ...
;     SEAM(2);
.LBB0_747:
	s_cmp_gt_i32 s75, 3
	v_readlane_b32 s2, v254, 40
	s_cselect_b64 s[0:1], -1, 0
	v_readlane_b32 s3, v254, 41
	s_and_b64 s[2:3], s[2:3], s[0:1]
	s_andn2_b64 vcc, exec, s[2:3]
	s_cbranch_vccnz .LBB0_799
	v_mov_b32_e32 v0, 0x20400
	ds_read_b32 v1, v0
	ds_read_b32 v2, v0 offset:4
	s_waitcnt vmcnt(0) lgkmcnt(0)
	v_readfirstlane_b32 s10, v1
	v_readfirstlane_b32 s11, v2
	s_cmp_eq_u32 s10, 0
	s_cbranch_scc1 .Lfb_old_2
	s_barrier
	v_readlane_b32 s14, v254, 4
	v_readlane_b32 s15, v254, 5
	s_cmp_lg_u64 s[14:15], 0
	s_cbranch_scc1 .Lfb_close_2
	s_mov_b64 s[12:13], exec
	s_mov_b64 exec, 1
	s_lshl_b32 s14, s92, 8
	s_add_u32 s38, s72, 0x311400
	s_addc_u32 s39, s73, 0
	s_add_u32 s38, s38, s14
	s_addc_u32 s39, s39, 0
	s_add_u32 s40, s72, 0x313400
	s_addc_u32 s41, s73, 0
	v_mov_b32_e32 v0, 0
	v_mov_b32_e32 v1, 1
	global_atomic_add v2, v0, v1, s[38:39] sc0
	s_sub_i32 s14, 3, s74
	s_mul_i32 s15, s14, s10
	s_mul_i32 s11, s14, s11
	s_waitcnt vmcnt(0)
	v_readfirstlane_b32 s14, v2
	s_add_i32 s14, s14, 1
	s_cmp_lg_u32 s14, s15
	s_cbranch_scc1 .Lfb_spin0_2
	buffer_wbl2 sc1
	s_waitcnt vmcnt(0)
	global_atomic_add v0, v1, s[40:41]

; __device__ __forceinline__ unsigned xb_ld(unsigned* p)              { return __hip_atomic_load(p, __ATOMIC_RELAXED, __HIP_MEMORY_SCOPE_AGENT); }
; __device__ __forceinline__ unsigned xb_add(unsigned* p, unsigned v) { return __hip_atomic_fetch_add(p, v, __ATOMIC_RELAXED, __HIP_MEMORY_SCOPE_AGENT); }
; #define XB_SPIN(cond, bar) do { unsigned _sp = 0; while (cond) { __builtin_amdgcn_s_sleep(1); \
;     if ((++_sp & 255u) == 0u) { if (xb_ld(&(bar)[XB_TMO])) break; if (_sp > XB_SPIN_CAP) { atomicAdd(&(bar)[XB_TMO], 1u); break; } } } } while (0)
; #define SEAM(k) do { if (IN(k) && IN((k) + 1)) { xcd_barrier(bar, wave == 0 && mk_lane() == 0); } } while (0)
; __device__ __forceinline__ void xcd_barrier(const XcdBarrier& b, bool leader) {
;     asm volatile("s_waitcnt vmcnt(0)" ::: "memory");
;     __syncthreads();
;     if (leader) {
;         unsigned* bar = b.bar;
;         __builtin_amdgcn_s_waitcnt(0);
;         unsigned nloc = b.st[0], nx = b.st[1];
;         if (nloc == 0u) { xcd_barrier_complete(bar, b.x, nloc, nx); b.st[0] = nloc; b.st[1] = nx; }
;         const unsigned old = xb_add(&bar[XB_XSUB(b.x)], 1u);
;         const unsigned gen = old / nloc;
;         if (old + 1u == (gen + 1u) * nloc) {
;             __builtin_amdgcn_fence(__ATOMIC_RELEASE, "agent");
;             asm volatile("s_waitcnt vmcnt(0)" ::: "memory");
;             const unsigned og = xb_add(&bar[XB_TOP], 1u);
;             const unsigned tg = og / nx;
;             if (og + 1u == (tg + 1u) * nx) xb_add(&bar[XB_TOPGEN], 1u);
;             else XB_SPIN(xb_ld(&bar[XB_TOPGEN]) == tg, bar);
;             __builtin_amdgcn_fence(__ATOMIC_ACQUIRE, "agent");
;             xb_add(&bar[XB_XGEN(b.x)], 1u);
; __global__ void __launch_bounds__(NWAVES * 64, 2) mk_fwd(Params P) {
;     ...
;     SEAM(3);
.LBB0_848:
	s_cmp_gt_i32 s75, 4
	s_cselect_b64 s[0:1], -1, 0
	s_and_b64 s[2:3], s[6:7], s[0:1]
	s_andn2_b64 vcc, exec, s[2:3]
	s_cbranch_vccnz .LBB0_900
	v_mov_b32_e32 v0, 0x20400
	ds_read_b32 v1, v0
	ds_read_b32 v2, v0 offset:4
	s_waitcnt vmcnt(0) lgkmcnt(0)
	v_readfirstlane_b32 s10, v1
	v_readfirstlane_b32 s11, v2
	s_cmp_eq_u32 s10, 0
	s_cbranch_scc1 .Lfb_old_3
	s_barrier
	v_readlane_b32 s14, v254, 4
	v_readlane_b32 s15, v254, 5
	s_cmp_lg_u64 s[14:15], 0
	s_cbranch_scc1 .Lfb_close_3
	s_mov_b64 s[12:13], exec
	s_mov_b64 exec, 1
	s_lshl_b32 s14, s92, 8
	s_add_u32 s38, s72, 0x311400
	s_addc_u32 s39, s73, 0
	s_add_u32 s38, s38, s14
	s_addc_u32 s39, s39, 0
	s_add_u32 s40, s72, 0x313400
	s_addc_u32 s41, s73, 0
	v_mov_b32_e32 v0, 0
	v_mov_b32_e32 v1, 1
	global_atomic_add v2, v0, v1, s[38:39] sc0
	s_sub_i32 s14, 4, s74
	s_mul_i32 s15, s14, s10
	s_mul_i32 s11, s14, s11
	s_waitcnt vmcnt(0)
	v_readfirstlane_b32 s14, v2
	s_add_i32 s14, s14, 1
	s_cmp_lg_u32 s14, s15
	s_cbranch_scc1 .Lfb_spin0_3
	buffer_wbl2 sc1
	s_waitcnt vmcnt(0)
	global_atomic_add v0, v1, s[40:41]

; __device__ __forceinline__ unsigned xb_ld(unsigned* p)              { return __hip_atomic_load(p, __ATOMIC_RELAXED, __HIP_MEMORY_SCOPE_AGENT); }
; __device__ __forceinline__ unsigned xb_add(unsigned* p, unsigned v) { return __hip_atomic_fetch_add(p, v, __ATOMIC_RELAXED, __HIP_MEMORY_SCOPE_AGENT); }
; #define XB_SPIN(cond, bar) do { unsigned _sp = 0; while (cond) { __builtin_amdgcn_s_sleep(1); \
;     if ((++_sp & 255u) == 0u) { if (xb_ld(&(bar)[XB_TMO])) break; if (_sp > XB_SPIN_CAP) { atomicAdd(&(bar)[XB_TMO], 1u); break; } } } } while (0)
; #define SEAM(k) do { if (IN(k) && IN((k) + 1)) { xcd_barrier(bar, wave == 0 && mk_lane() == 0); } } while (0)
; __device__ __forceinline__ void xcd_barrier(const XcdBarrier& b, bool leader) {
;     asm volatile("s_waitcnt vmcnt(0)" ::: "memory");
;     __syncthreads();
;     if (leader) {
;         unsigned* bar = b.bar;
;         __builtin_amdgcn_s_waitcnt(0);
;         unsigned nloc = b.st[0], nx = b.st[1];
;         if (nloc == 0u) { xcd_barrier_complete(bar, b.x, nloc, nx); b.st[0] = nloc; b.st[1] = nx; }
;         const unsigned old = xb_add(&bar[XB_XSUB(b.x)], 1u);
;         const unsigned gen = old / nloc;
;         if (old + 1u == (gen + 1u) * nloc) {
;             __builtin_amdgcn_fence(__ATOMIC_RELEASE, "agent");
;             asm volatile("s_waitcnt vmcnt(0)" ::: "memory");
;             const unsigned og = xb_add(&bar[XB_TOP], 1u);
;             const unsigned tg = og / nx;
;             if (og + 1u == (tg + 1u) * nx) xb_add(&bar[XB_TOPGEN], 1u);
;             else XB_SPIN(xb_ld(&bar[XB_TOPGEN]) == tg, bar);
;             __builtin_amdgcn_fence(__ATOMIC_ACQUIRE, "agent");
;             xb_add(&bar[XB_XGEN(b.x)], 1u);
; __global__ void __launch_bounds__(NWAVES * 64, 2) mk_fwd(Params P) {
;     ...
;     SEAM(4);
.LBB0_939:
	s_cmp_gt_i32 s75, 5
	s_cselect_b64 s[4:5], -1, 0
	s_and_b64 s[0:1], s[0:1], s[4:5]
	s_andn2_b64 vcc, exec, s[0:1]
	s_cbranch_vccnz .LBB0_991
	v_mov_b32_e32 v0, 0x20400
	ds_read_b32 v1, v0
	ds_read_b32 v2, v0 offset:4
	s_waitcnt vmcnt(0) lgkmcnt(0)
	v_readfirstlane_b32 s10, v1
	v_readfirstlane_b32 s11, v2
	s_cmp_eq_u32 s10, 0
	s_cbranch_scc1 .Lfb_old_4
	s_barrier
	v_readlane_b32 s14, v254, 4
	v_readlane_b32 s15, v254, 5
	s_cmp_lg_u64 s[14:15], 0
	s_cbranch_scc1 .Lfb_close_4
	s_mov_b64 s[12:13], exec
	s_mov_b64 exec, 1
	s_lshl_b32 s14, s92, 8
	s_add_u32 s38, s72, 0x311400
	s_addc_u32 s39, s73, 0
	s_add_u32 s38, s38, s14
	s_addc_u32 s39, s39, 0
	s_add_u32 s40, s72, 0x313400
	s_addc_u32 s41, s73, 0
	v_mov_b32_e32 v0, 0
	v_mov_b32_e32 v1, 1
	global_atomic_add v2, v0, v1, s[38:39] sc0
	s_sub_i32 s14, 5, s74
	s_mul_i32 s15, s14, s10
	s_mul_i32 s11, s14, s11
	s_waitcnt vmcnt(0)
	v_readfirstlane_b32 s14, v2
	s_add_i32 s14, s14, 1
	s_cmp_lg_u32 s14, s15
	s_cbranch_scc1 .Lfb_spin0_4
	buffer_wbl2 sc1
	s_waitcnt vmcnt(0)
	global_atomic_add v0, v1, s[40:41]

; __device__ __forceinline__ void xcd_barrier(const XcdBarrier& b, bool leader) {
;     asm volatile("s_waitcnt vmcnt(0)" ::: "memory");
;     __syncthreads();
;     if (leader) {
;         unsigned* bar = b.bar;
;         __builtin_amdgcn_s_waitcnt(0);
;         unsigned nloc = b.st[0], nx = b.st[1];
;         if (nloc == 0u) { xcd_barrier_complete(bar, b.x, nloc, nx); b.st[0] = nloc; b.st[1] = nx; }
.Lfb_old_4:
	v_readlane_b32 s0, v254, 4
	v_readlane_b32 s1, v254, 5
	s_and_b64 vcc, exec, s[0:1]
	s_mov_b64 s[6:7], 0
	s_cbranch_vccnz .LBB0_942
	v_mov_b32_e32 v0, v212
	s_nop 0
	v_cmp_eq_u32_e32 vcc, 0, v0
	s_and_b64 s[6:7], vcc, exec

; __device__ __forceinline__ unsigned xb_ld(unsigned* p)              { return __hip_atomic_load(p, __ATOMIC_RELAXED, __HIP_MEMORY_SCOPE_AGENT); }
; __device__ __forceinline__ unsigned xb_add(unsigned* p, unsigned v) { return __hip_atomic_fetch_add(p, v, __ATOMIC_RELAXED, __HIP_MEMORY_SCOPE_AGENT); }
; #define XB_SPIN(cond, bar) do { unsigned _sp = 0; while (cond) { __builtin_amdgcn_s_sleep(1); \
;     if ((++_sp & 255u) == 0u) { if (xb_ld(&(bar)[XB_TMO])) break; if (_sp > XB_SPIN_CAP) { atomicAdd(&(bar)[XB_TMO], 1u); break; } } } } while (0)
; #define SEAM(k) do { if (IN(k) && IN((k) + 1)) { xcd_barrier(bar, wave == 0 && mk_lane() == 0); } } while (0)
; __device__ __forceinline__ void xcd_barrier(const XcdBarrier& b, bool leader) {
;     asm volatile("s_waitcnt vmcnt(0)" ::: "memory");
;     __syncthreads();
;     if (leader) {
;         unsigned* bar = b.bar;
;         __builtin_amdgcn_s_waitcnt(0);
;         unsigned nloc = b.st[0], nx = b.st[1];
;         if (nloc == 0u) { xcd_barrier_complete(bar, b.x, nloc, nx); b.st[0] = nloc; b.st[1] = nx; }
;         const unsigned old = xb_add(&bar[XB_XSUB(b.x)], 1u);
;         const unsigned gen = old / nloc;
;         if (old + 1u == (gen + 1u) * nloc) {
;             __builtin_amdgcn_fence(__ATOMIC_RELEASE, "agent");
;             asm volatile("s_waitcnt vmcnt(0)" ::: "memory");
;             const unsigned og = xb_add(&bar[XB_TOP], 1u);
;             const unsigned tg = og / nx;
;             if (og + 1u == (tg + 1u) * nx) xb_add(&bar[XB_TOPGEN], 1u);
;             else XB_SPIN(xb_ld(&bar[XB_TOPGEN]) == tg, bar);
;             __builtin_amdgcn_fence(__ATOMIC_ACQUIRE, "agent");
;             xb_add(&bar[XB_XGEN(b.x)], 1u);
; __global__ void __launch_bounds__(NWAVES * 64, 2) mk_fwd(Params P) {
;     ...
;     SEAM(5);
.LBB0_1089:
	s_cmp_gt_i32 s75, 6
	s_cselect_b64 s[0:1], -1, 0
	s_and_b64 s[2:3], s[36:37], s[0:1]
	s_andn2_b64 vcc, exec, s[2:3]
	s_cbranch_vccnz .LBB0_1141
	v_mov_b32_e32 v0, 0x20400
	ds_read_b32 v1, v0
	ds_read_b32 v2, v0 offset:4
	s_waitcnt vmcnt(0) lgkmcnt(0)
	v_readfirstlane_b32 s10, v1
	v_readfirstlane_b32 s11, v2
	s_cmp_eq_u32 s10, 0
	s_cbranch_scc1 .Lfb_old_5
	s_barrier
	v_readlane_b32 s14, v254, 4
	v_readlane_b32 s15, v254, 5
	s_cmp_lg_u64 s[14:15], 0
	s_cbranch_scc1 .Lfb_close_5
	s_mov_b64 s[12:13], exec
	s_mov_b64 exec, 1
	s_lshl_b32 s14, s92, 8
	s_add_u32 s38, s72, 0x311400
	s_addc_u32 s39, s73, 0
	s_add_u32 s38, s38, s14
	s_addc_u32 s39, s39, 0
	s_add_u32 s40, s72, 0x313400
	s_addc_u32 s41, s73, 0
	v_mov_b32_e32 v0, 0
	v_mov_b32_e32 v1, 1
	global_atomic_add v2, v0, v1, s[38:39] sc0
	s_sub_i32 s14, 6, s74
	s_mul_i32 s15, s14, s10
	s_mul_i32 s11, s14, s11
	s_waitcnt vmcnt(0)
	v_readfirstlane_b32 s14, v2
	s_add_i32 s14, s14, 1
	s_cmp_lg_u32 s14, s15
	s_cbranch_scc1 .Lfb_spin0_5
	buffer_wbl2 sc1
	s_waitcnt vmcnt(0)
	global_atomic_add v0, v1, s[40:41]

; __device__ __forceinline__ unsigned xb_ld(unsigned* p)              { return __hip_atomic_load(p, __ATOMIC_RELAXED, __HIP_MEMORY_SCOPE_AGENT); }
; __device__ __forceinline__ unsigned xb_add(unsigned* p, unsigned v) { return __hip_atomic_fetch_add(p, v, __ATOMIC_RELAXED, __HIP_MEMORY_SCOPE_AGENT); }
; #define XB_SPIN(cond, bar) do { unsigned _sp = 0; while (cond) { __builtin_amdgcn_s_sleep(1); \
;     if ((++_sp & 255u) == 0u) { if (xb_ld(&(bar)[XB_TMO])) break; if (_sp > XB_SPIN_CAP) { atomicAdd(&(bar)[XB_TMO], 1u); break; } } } } while (0)
; #define SEAM(k) do { if (IN(k) && IN((k) + 1)) { xcd_barrier(bar, wave == 0 && mk_lane() == 0); } } while (0)
; __device__ __forceinline__ void xcd_barrier(const XcdBarrier& b, bool leader) {
;     asm volatile("s_waitcnt vmcnt(0)" ::: "memory");
;     __syncthreads();
;     if (leader) {
;         unsigned* bar = b.bar;
;         __builtin_amdgcn_s_waitcnt(0);
;         unsigned nloc = b.st[0], nx = b.st[1];
;         if (nloc == 0u) { xcd_barrier_complete(bar, b.x, nloc, nx); b.st[0] = nloc; b.st[1] = nx; }
;         const unsigned old = xb_add(&bar[XB_XSUB(b.x)], 1u);
;         const unsigned gen = old / nloc;
;         if (old + 1u == (gen + 1u) * nloc) {
;             __builtin_amdgcn_fence(__ATOMIC_RELEASE, "agent");
;             asm volatile("s_waitcnt vmcnt(0)" ::: "memory");
;             const unsigned og = xb_add(&bar[XB_TOP], 1u);
;             const unsigned tg = og / nx;
;             if (og + 1u == (tg + 1u) * nx) xb_add(&bar[XB_TOPGEN], 1u);
;             else XB_SPIN(xb_ld(&bar[XB_TOPGEN]) == tg, bar);
;             __builtin_amdgcn_fence(__ATOMIC_ACQUIRE, "agent");
;             xb_add(&bar[XB_XGEN(b.x)], 1u);
; __global__ void __launch_bounds__(NWAVES * 64, 2) mk_fwd(Params P) {
;     ...
;     SEAM(6);
.LBB0_1147:
	s_cmp_gt_i32 s75, 7
	s_cselect_b64 s[4:5], -1, 0
	s_and_b64 s[0:1], s[0:1], s[4:5]
	s_andn2_b64 vcc, exec, s[0:1]
	s_cbranch_vccnz .LBB0_1199
	v_mov_b32_e32 v0, 0x20400
	ds_read_b32 v1, v0
	ds_read_b32 v2, v0 offset:4
	s_waitcnt vmcnt(0) lgkmcnt(0)
	v_readfirstlane_b32 s10, v1
	v_readfirstlane_b32 s11, v2
	s_cmp_eq_u32 s10, 0
	s_cbranch_scc1 .Lfb_old_6
	s_barrier
	v_readlane_b32 s14, v254, 4
	v_readlane_b32 s15, v254, 5
	s_cmp_lg_u64 s[14:15], 0
	s_cbranch_scc1 .Lfb_close_6
	s_mov_b64 s[12:13], exec
	s_mov_b64 exec, 1
	s_lshl_b32 s14, s92, 8
	s_add_u32 s38, s72, 0x311400
	s_addc_u32 s39, s73, 0
	s_add_u32 s38, s38, s14
	s_addc_u32 s39, s39, 0
	s_add_u32 s40, s72, 0x313400
	s_addc_u32 s41, s73, 0
	v_mov_b32_e32 v0, 0
	v_mov_b32_e32 v1, 1
	global_atomic_add v2, v0, v1, s[38:39] sc0
	s_sub_i32 s14, 7, s74
	s_mul_i32 s15, s14, s10
	s_mul_i32 s11, s14, s11
	s_waitcnt vmcnt(0)
	v_readfirstlane_b32 s14, v2
	s_add_i32 s14, s14, 1
	s_cmp_lg_u32 s14, s15
	s_cbranch_scc1 .Lfb_spin0_6
	buffer_wbl2 sc1
	s_waitcnt vmcnt(0)
	global_atomic_add v0, v1, s[40:41]

; __device__ __forceinline__ unsigned xb_ld(unsigned* p)              { return __hip_atomic_load(p, __ATOMIC_RELAXED, __HIP_MEMORY_SCOPE_AGENT); }
; __device__ __forceinline__ unsigned xb_add(unsigned* p, unsigned v) { return __hip_atomic_fetch_add(p, v, __ATOMIC_RELAXED, __HIP_MEMORY_SCOPE_AGENT); }
; #define XB_SPIN(cond, bar) do { unsigned _sp = 0; while (cond) { __builtin_amdgcn_s_sleep(1); \
;     if ((++_sp & 255u) == 0u) { if (xb_ld(&(bar)[XB_TMO])) break; if (_sp > XB_SPIN_CAP) { atomicAdd(&(bar)[XB_TMO], 1u); break; } } } } while (0)
; #define SEAM(k) do { if (IN(k) && IN((k) + 1)) { xcd_barrier(bar, wave == 0 && mk_lane() == 0); } } while (0)
; __device__ __forceinline__ void xcd_barrier(const XcdBarrier& b, bool leader) {
;     asm volatile("s_waitcnt vmcnt(0)" ::: "memory");
;     __syncthreads();
;     if (leader) {
;         unsigned* bar = b.bar;
;         __builtin_amdgcn_s_waitcnt(0);
;         unsigned nloc = b.st[0], nx = b.st[1];
;         if (nloc == 0u) { xcd_barrier_complete(bar, b.x, nloc, nx); b.st[0] = nloc; b.st[1] = nx; }
;         const unsigned old = xb_add(&bar[XB_XSUB(b.x)], 1u);
;         const unsigned gen = old / nloc;
;         if (old + 1u == (gen + 1u) * nloc) {
;             __builtin_amdgcn_fence(__ATOMIC_RELEASE, "agent");
;             asm volatile("s_waitcnt vmcnt(0)" ::: "memory");
;             const unsigned og = xb_add(&bar[XB_TOP], 1u);
;             const unsigned tg = og / nx;
;             if (og + 1u == (tg + 1u) * nx) xb_add(&bar[XB_TOPGEN], 1u);
;             else XB_SPIN(xb_ld(&bar[XB_TOPGEN]) == tg, bar);
;             __builtin_amdgcn_fence(__ATOMIC_ACQUIRE, "agent");
;             xb_add(&bar[XB_XGEN(b.x)], 1u);
; __global__ void __launch_bounds__(NWAVES * 64, 2) mk_fwd(Params P) {
;     ...
;     SEAM(7);
.LBB0_1238:
	s_cmp_gt_i32 s75, 8
	s_cselect_b64 s[4:5], -1, 0
	s_and_b64 s[0:1], s[0:1], s[4:5]
	s_andn2_b64 vcc, exec, s[0:1]
	s_cbranch_vccnz .LBB0_1290
	v_mov_b32_e32 v0, 0x20400
	ds_read_b32 v1, v0
	ds_read_b32 v2, v0 offset:4
	s_waitcnt vmcnt(0) lgkmcnt(0)
	v_readfirstlane_b32 s10, v1
	v_readfirstlane_b32 s11, v2
	s_cmp_eq_u32 s10, 0
	s_cbranch_scc1 .Lfb_old_7
	s_barrier
	v_readlane_b32 s14, v254, 4
	v_readlane_b32 s15, v254, 5
	s_cmp_lg_u64 s[14:15], 0
	s_cbranch_scc1 .Lfb_close_7
	s_mov_b64 s[12:13], exec
	s_mov_b64 exec, 1
	s_lshl_b32 s14, s92, 8
	s_add_u32 s38, s72, 0x311400
	s_addc_u32 s39, s73, 0
	s_add_u32 s38, s38, s14
	s_addc_u32 s39, s39, 0
	s_add_u32 s40, s72, 0x313400
	s_addc_u32 s41, s73, 0
	v_mov_b32_e32 v0, 0
	v_mov_b32_e32 v1, 1
	global_atomic_add v2, v0, v1, s[38:39] sc0
	s_sub_i32 s14, 8, s74
	s_mul_i32 s15, s14, s10
	s_mul_i32 s11, s14, s11
	s_waitcnt vmcnt(0)
	v_readfirstlane_b32 s14, v2
	s_add_i32 s14, s14, 1
	s_cmp_lg_u32 s14, s15
	s_cbranch_scc1 .Lfb_spin0_7
	buffer_wbl2 sc1
	s_waitcnt vmcnt(0)
	global_atomic_add v0, v1, s[40:41]

; __device__ __forceinline__ unsigned xb_ld(unsigned* p)              { return __hip_atomic_load(p, __ATOMIC_RELAXED, __HIP_MEMORY_SCOPE_AGENT); }
; __device__ __forceinline__ unsigned xb_add(unsigned* p, unsigned v) { return __hip_atomic_fetch_add(p, v, __ATOMIC_RELAXED, __HIP_MEMORY_SCOPE_AGENT); }
; #define XB_SPIN(cond, bar) do { unsigned _sp = 0; while (cond) { __builtin_amdgcn_s_sleep(1); \
;     if ((++_sp & 255u) == 0u) { if (xb_ld(&(bar)[XB_TMO])) break; if (_sp > XB_SPIN_CAP) { atomicAdd(&(bar)[XB_TMO], 1u); break; } } } } while (0)
; #define SEAM(k) do { if (IN(k) && IN((k) + 1)) { xcd_barrier(bar, wave == 0 && mk_lane() == 0); } } while (0)
; __device__ __forceinline__ void xcd_barrier(const XcdBarrier& b, bool leader) {
;     asm volatile("s_waitcnt vmcnt(0)" ::: "memory");
;     __syncthreads();
;     if (leader) {
;         unsigned* bar = b.bar;
;         __builtin_amdgcn_s_waitcnt(0);
;         unsigned nloc = b.st[0], nx = b.st[1];
;         if (nloc == 0u) { xcd_barrier_complete(bar, b.x, nloc, nx); b.st[0] = nloc; b.st[1] = nx; }
;         const unsigned old = xb_add(&bar[XB_XSUB(b.x)], 1u);
;         const unsigned gen = old / nloc;
;         if (old + 1u == (gen + 1u) * nloc) {
;             __builtin_amdgcn_fence(__ATOMIC_RELEASE, "agent");
;             asm volatile("s_waitcnt vmcnt(0)" ::: "memory");
;             const unsigned og = xb_add(&bar[XB_TOP], 1u);
;             const unsigned tg = og / nx;
;             if (og + 1u == (tg + 1u) * nx) xb_add(&bar[XB_TOPGEN], 1u);
;             else XB_SPIN(xb_ld(&bar[XB_TOPGEN]) == tg, bar);
;             __builtin_amdgcn_fence(__ATOMIC_ACQUIRE, "agent");
;             xb_add(&bar[XB_XGEN(b.x)], 1u);
; __global__ void __launch_bounds__(NWAVES * 64, 2) mk_fwd(Params P) {
;     ...
;     SEAM(8);
.LBB0_1388:
	s_cmp_gt_i32 s75, 9
	s_cselect_b64 s[0:1], -1, 0
	s_and_b64 s[2:3], s[36:37], s[0:1]
	s_andn2_b64 vcc, exec, s[2:3]
	s_cbranch_vccnz .LBB0_1440
	v_mov_b32_e32 v0, 0x20400
	ds_read_b32 v1, v0
	ds_read_b32 v2, v0 offset:4
	s_waitcnt vmcnt(0) lgkmcnt(0)
	v_readfirstlane_b32 s10, v1
	v_readfirstlane_b32 s11, v2
	s_cmp_eq_u32 s10, 0
	s_cbranch_scc1 .Lfb_old_8
	s_barrier
	v_readlane_b32 s14, v254, 4
	v_readlane_b32 s15, v254, 5
	s_cmp_lg_u64 s[14:15], 0
	s_cbranch_scc1 .Lfb_close_8
	s_mov_b64 s[12:13], exec
	s_mov_b64 exec, 1
	s_lshl_b32 s14, s92, 8
	s_add_u32 s38, s72, 0x311400
	s_addc_u32 s39, s73, 0
	s_add_u32 s38, s38, s14
	s_addc_u32 s39, s39, 0
	s_add_u32 s40, s72, 0x313400
	s_addc_u32 s41, s73, 0
	v_mov_b32_e32 v0, 0
	v_mov_b32_e32 v1, 1
	global_atomic_add v2, v0, v1, s[38:39] sc0
	s_sub_i32 s14, 9, s74
	s_mul_i32 s15, s14, s10
	s_mul_i32 s11, s14, s11
	s_waitcnt vmcnt(0)
	v_readfirstlane_b32 s14, v2
	s_add_i32 s14, s14, 1
	s_cmp_lg_u32 s14, s15
	s_cbranch_scc1 .Lfb_spin0_8
	buffer_wbl2 sc1
	s_waitcnt vmcnt(0)
	global_atomic_add v0, v1, s[40:41]

; __device__ __forceinline__ unsigned xb_ld(unsigned* p)              { return __hip_atomic_load(p, __ATOMIC_RELAXED, __HIP_MEMORY_SCOPE_AGENT); }
; __device__ __forceinline__ unsigned xb_add(unsigned* p, unsigned v) { return __hip_atomic_fetch_add(p, v, __ATOMIC_RELAXED, __HIP_MEMORY_SCOPE_AGENT); }
; #define XB_SPIN(cond, bar) do { unsigned _sp = 0; while (cond) { __builtin_amdgcn_s_sleep(1); \
;     if ((++_sp & 255u) == 0u) { if (xb_ld(&(bar)[XB_TMO])) break; if (_sp > XB_SPIN_CAP) { atomicAdd(&(bar)[XB_TMO], 1u); break; } } } } while (0)
; #define SEAM(k) do { if (IN(k) && IN((k) + 1)) { xcd_barrier(bar, wave == 0 && mk_lane() == 0); } } while (0)
; __device__ __forceinline__ void xcd_barrier(const XcdBarrier& b, bool leader) {
;     asm volatile("s_waitcnt vmcnt(0)" ::: "memory");
;     __syncthreads();
;     if (leader) {
;         unsigned* bar = b.bar;
;         __builtin_amdgcn_s_waitcnt(0);
;         unsigned nloc = b.st[0], nx = b.st[1];
;         if (nloc == 0u) { xcd_barrier_complete(bar, b.x, nloc, nx); b.st[0] = nloc; b.st[1] = nx; }
;         const unsigned old = xb_add(&bar[XB_XSUB(b.x)], 1u);
;         const unsigned gen = old / nloc;
;         if (old + 1u == (gen + 1u) * nloc) {
;             __builtin_amdgcn_fence(__ATOMIC_RELEASE, "agent");
;             asm volatile("s_waitcnt vmcnt(0)" ::: "memory");
;             const unsigned og = xb_add(&bar[XB_TOP], 1u);
;             const unsigned tg = og / nx;
;             if (og + 1u == (tg + 1u) * nx) xb_add(&bar[XB_TOPGEN], 1u);
;             else XB_SPIN(xb_ld(&bar[XB_TOPGEN]) == tg, bar);
;             __builtin_amdgcn_fence(__ATOMIC_ACQUIRE, "agent");
;             xb_add(&bar[XB_XGEN(b.x)], 1u);
; __global__ void __launch_bounds__(NWAVES * 64, 2) mk_fwd(Params P) {
;     ...
;     SEAM(9);
.LBB0_1479:
	s_cmp_gt_i32 s75, 10
	s_cselect_b64 s[4:5], -1, 0
	s_and_b64 s[0:1], s[0:1], s[4:5]
	s_andn2_b64 vcc, exec, s[0:1]
	s_cbranch_vccnz .LBB0_1531
	v_mov_b32_e32 v0, 0x20400
	ds_read_b32 v1, v0
	ds_read_b32 v2, v0 offset:4
	s_waitcnt vmcnt(0) lgkmcnt(0)
	v_readfirstlane_b32 s10, v1
	v_readfirstlane_b32 s11, v2
	s_cmp_eq_u32 s10, 0
	s_cbranch_scc1 .Lfb_old_9
	s_barrier
	v_readlane_b32 s14, v254, 4
	v_readlane_b32 s15, v254, 5
	s_cmp_lg_u64 s[14:15], 0
	s_cbranch_scc1 .Lfb_close_9
	s_mov_b64 s[12:13], exec
	s_mov_b64 exec, 1
	s_lshl_b32 s14, s92, 8
	s_add_u32 s38, s72, 0x311400
	s_addc_u32 s39, s73, 0
	s_add_u32 s38, s38, s14
	s_addc_u32 s39, s39, 0
	s_add_u32 s40, s72, 0x313400
	s_addc_u32 s41, s73, 0
	v_mov_b32_e32 v0, 0
	v_mov_b32_e32 v1, 1
	global_atomic_add v2, v0, v1, s[38:39] sc0
	s_sub_i32 s14, 10, s74
	s_mul_i32 s15, s14, s10
	s_mul_i32 s11, s14, s11
	s_waitcnt vmcnt(0)
	v_readfirstlane_b32 s14, v2
	s_add_i32 s14, s14, 1
	s_cmp_lg_u32 s14, s15
	s_cbranch_scc1 .Lfb_spin0_9
	buffer_wbl2 sc1
	s_waitcnt vmcnt(0)
	global_atomic_add v0, v1, s[40:41]
